# weight-conversion units dealt early: 48 workgroups run the cvt loop before their attention units so HBM streaming overlaps attention compute (on top of v024)
# baseline (speedup 1.0000x reference)
; #define DEAL_LOOP(F, ctr, N, BODY) do { gu32* _c = (ctr); int u = F.bid; while (u < (N)) { const unsigned _t = deal_prefetch(F, _c); BODY; u = deal_publish(F, _t) + F.G; } __syncthreads(); } while (0)
; #define LAUNDER() do { launder(F); GAS unsigned char* _g = (GAS unsigned char*)ws; asm volatile("" : "+s"(_g)); ws = (unsigned char*)_g; } while (0)
; __global__ void __launch_bounds__(NTHR, 2) fwd(Args args) {
;     ...
;             if (ATTN_VAR) { LAUNDER(); DEAL_LOOP(F, cnt_word(F, l, CNT_ATTN + 5), AT_UNITS, attn_unit<ATTN_VAR>(args, F, l, u)); xcd_barrier(bar); }
;             for (int rep = 0; rep < REPS(8); ++rep) { LAUNDER();
;                 if (PH_ON(8)) DEAL_LOOP(F, cnt_word(F, l, CNT_ATTN + 5 * rep), AT_UNITS, attn_unit<0>(args, F, l, u));
.LBB0_1366:
	s_or_b64 exec, exec, s[2:3]
	s_and_b32 s101, s69, 0x18
	s_cmp_lg_u32 s101, 0
	s_cbranch_scc1 .Lecvt_skip
	s_cmpk_ge_i32 s69, 0xa8
	s_cbranch_scc1 .Lecvt_skip
	s_lshl_b32 s0, s90, 12
	s_add_u32 s0, s74, s0
	s_addc_u32 s1, s75, 0
	s_add_u32 s0, s0, 0x10000
	s_addc_u32 s1, s1, 0
	v_writelane_b32 v249, s0, 33
	v_writelane_b32 v249, s1, 34
	v_writelane_b32 v249, s90, 37
	v_writelane_b32 v249, s91, 38
	s_lshl_b32 s0, s90, 8
	v_writelane_b32 v249, s0, 29
	v_writelane_b32 v249, s63, 30
	s_mov_b32 s100, 1
	s_branch .Lcvt_entry
.Lecvt_ret:
	s_mov_b32 s100, 0
	s_mov_b32 s67, 0xf800000
	s_mov_b32 s65, 0x5d800000
	s_mov_b32 s60, 0xf149f2ca
.Lecvt_skip:
	s_lshl_b32 s4, s90, 10
	v_readlane_b32 s0, v249, 25
	s_add_u32 s0, s74, s0
	s_mov_b32 s5, s63
	v_writelane_b32 v249, s0, 31
	s_addc_u32 s0, s75, 0
	s_cmpk_lt_i32 s69, 0x240
	v_cmp_eq_u32_e64 s[36:37], 0, v0
	v_writelane_b32 v249, s0, 32
	s_cbranch_scc0 .LBB0_1420
	s_lshl_b64 s[0:1], s[4:5], 2
	s_add_u32 s0, s74, s0
	s_addc_u32 s1, s75, s1
	s_add_u32 s6, s0, 0x10200
	s_addc_u32 s7, s1, 0
	v_readlane_b32 s2, v249, 31
	s_add_u32 s8, s2, 0x3b86000
	v_readlane_b32 s3, v249, 32
	v_readlane_b32 s12, v250, 60
	s_addc_u32 s9, s3, 0
	s_lshl_b32 s62, s90, 6
	v_readlane_b32 s22, v251, 6
	v_readlane_b32 s23, v251, 7
	v_readlane_b32 s26, v251, 10
	v_readlane_b32 s27, v251, 11
	s_lshl_b32 s33, s90, 24
	s_lshl_b64 s[0:1], s[62:63], 2
	s_mov_b64 s[22:23], s[26:27]
	s_add_u32 s10, s22, s0
	s_addc_u32 s11, s23, s1
	v_readlane_b32 s13, v250, 61
	v_readlane_b32 s20, v251, 4
	s_add_u32 s12, s2, 0x3b86004
	s_addc_u32 s13, s3, 0
	s_mov_b32 s20, s69
	v_readlane_b32 s14, v250, 62
	v_readlane_b32 s15, v250, 63
	v_readlane_b32 s16, v251, 0
	v_readlane_b32 s17, v251, 1
	v_readlane_b32 s18, v251, 2
	v_readlane_b32 s19, v251, 3
	v_readlane_b32 s21, v251, 5
	v_readlane_b32 s24, v251, 8
	v_readlane_b32 s25, v251, 9
	s_branch .LBB0_1369

; #define DEAL_LOOP_DYN(F, ctr, N, BODY) do { gu32* _c = (ctr); int u = next_unit(F, _c); while (u < (N)) { const unsigned _t = deal_prefetch(F, _c); BODY; u = deal_publish(F, _t); } __syncthreads(); } while (0)
; #define LAUNDER() do { launder(F); GAS unsigned char* _g = (GAS unsigned char*)ws; asm volatile("" : "+s"(_g)); ws = (unsigned char*)_g; } while (0)
; DI int next_unit(const Frame& F, gu32* ctr) {
;     __syncthreads();
;     if (F.tid == 0) F.MISC[4] = __hip_atomic_fetch_add(ctr, 1u, RLX_AGENT);
;     __syncthreads();
;     return __builtin_amdgcn_readfirstlane((int)F.MISC[4]);
; }
; __global__ void __launch_bounds__(NTHR, 2) fwd(Args args) {
;     ...
;             { LAUNDER(); const int cv0 = BT_EARLY + l * BT_LAYER, cvn = ((l + 1 < DEPTH ? BT_LAYER : BT_LAYER - BT_EARLY)) / CV_PER;
;               DEAL_LOOP_DYN(F, cnt_word(F, l, CNT_CVT), cvn, cvt_unit(args, F, cv0 + u * CV_PER)); }
.Lcvt_entry:
	v_cmp_eq_u32_e64 s[8:9], 0, v0
	s_barrier
	s_and_saveexec_b64 s[0:1], s[8:9]
	v_writelane_b32 v249, s69, 53
	v_writelane_b32 v249, s78, 54
	s_xor_b64 s[0:1], exec, s[0:1]
	s_mov_b32 s33, 0x400000
	v_writelane_b32 v249, s79, 55
	v_writelane_b32 v249, s96, 56
	s_nop 1
	v_writelane_b32 v249, s97, 57
	v_writelane_b32 v249, s8, 45
	s_nop 1
	v_writelane_b32 v249, s9, 46
	s_cbranch_execz .LBB0_1572
	s_mov_b64 s[4:5], exec
	v_mbcnt_lo_u32_b32 v3, s4, 0
	v_mbcnt_hi_u32_b32 v3, s5, v3
	v_cmp_eq_u32_e32 vcc, 0, v3
	s_and_saveexec_b64 s[2:3], vcc
	s_cbranch_execz .LBB0_1571
	s_bcnt1_i32_b64 s4, s[4:5]
	v_mov_b32_e32 v4, s4
	v_readlane_b32 s4, v249, 33
	v_readlane_b32 s5, v249, 34
	s_nop 4
	global_atomic_add v4, v2, v4, s[4:5] offset:2816 sc0
